# P6 (MLP-in) epilogue: 8 row-norm loads up front, counted vmcnt so stores are never acknowledged in the critical path
# baseline (speedup 1.0000x reference)
.LBB0_667:
	v_lshl_add_u32 v222, s77, 8, v154
	v_lshlrev_b32_e32 v223, 2, v222
	s_lshl_b32 s14, s76, 9
	v_lshl_add_u32 v224, v222, 13, v132
	v_add_u32_e32 v224, s14, v224
	global_load_dword v166, v223, s[6:7]
	global_load_dword v168, v223, s[6:7] offset:64
	global_load_dword v170, v223, s[6:7] offset:128
	global_load_dword v172, v223, s[6:7] offset:192
	global_load_dword v174, v223, s[6:7] offset:512
	global_load_dword v176, v223, s[6:7] offset:576
	global_load_dword v178, v223, s[6:7] offset:640
	global_load_dword v180, v223, s[6:7] offset:704
	s_waitcnt vmcnt(7)
	v_fmamk_f32 v166, v166, 0x3a800000, v148
	v_rsq_f32_e32 v166, v166
	s_nop 0
	v_pk_mul_f32 v[124:125], v[124:125], v[166:167] op_sel_hi:[1,0]
	v_pk_mul_f32 v[126:127], v[126:127], v[166:167] op_sel_hi:[1,0]
	v_pk_mul_f32 v[120:121], v[120:121], v[166:167] op_sel_hi:[1,0]
	v_pk_mul_f32 v[122:123], v[122:123], v[166:167] op_sel_hi:[1,0]
	v_pk_mul_f32 v[116:117], v[116:117], v[166:167] op_sel_hi:[1,0]
	v_pk_mul_f32 v[118:119], v[118:119], v[166:167] op_sel_hi:[1,0]
	v_pk_mul_f32 v[112:113], v[112:113], v[166:167] op_sel_hi:[1,0]
	v_pk_mul_f32 v[114:115], v[114:115], v[166:167] op_sel_hi:[1,0]
	v_max_f32_e32 v124, 0, v124
	v_max_f32_e32 v125, 0, v125
	v_max_f32_e32 v126, 0, v126
	v_max_f32_e32 v127, 0, v127
	v_max_f32_e32 v120, 0, v120
	v_max_f32_e32 v121, 0, v121
	v_max_f32_e32 v122, 0, v122
	v_max_f32_e32 v123, 0, v123
	v_max_f32_e32 v116, 0, v116
	v_max_f32_e32 v117, 0, v117
	v_max_f32_e32 v118, 0, v118
	v_max_f32_e32 v119, 0, v119
	v_max_f32_e32 v112, 0, v112
	v_max_f32_e32 v113, 0, v113
	v_max_f32_e32 v114, 0, v114
	v_max_f32_e32 v115, 0, v115
	v_pk_mul_f32 v[124:125], v[124:125], v[124:125]
	v_pk_mul_f32 v[126:127], v[126:127], v[126:127]
	v_pk_mul_f32 v[120:121], v[120:121], v[120:121]
	v_pk_mul_f32 v[122:123], v[122:123], v[122:123]
	v_pk_mul_f32 v[116:117], v[116:117], v[116:117]
	v_pk_mul_f32 v[118:119], v[118:119], v[118:119]
	v_pk_mul_f32 v[112:113], v[112:113], v[112:113]
	v_pk_mul_f32 v[114:115], v[114:115], v[114:115]
	v_cvt_pk_bf16_f32 v124, v124, v125
	v_cvt_pk_bf16_f32 v125, v126, v127
	v_cvt_pk_bf16_f32 v126, v120, v121
	v_cvt_pk_bf16_f32 v127, v122, v123
	v_cvt_pk_bf16_f32 v116, v116, v117
	v_cvt_pk_bf16_f32 v117, v118, v119
	v_cvt_pk_bf16_f32 v118, v112, v113
	v_cvt_pk_bf16_f32 v119, v114, v115
	global_store_dwordx4 v224, v[124:127], s[48:49]
	global_store_dwordx4 v224, v[116:119], s[48:49] offset:256
	s_waitcnt vmcnt(8)
	v_fmamk_f32 v168, v168, 0x3a800000, v148
	v_rsq_f32_e32 v168, v168
	s_nop 0
	v_pk_mul_f32 v[108:109], v[108:109], v[168:169] op_sel_hi:[1,0]
	v_pk_mul_f32 v[110:111], v[110:111], v[168:169] op_sel_hi:[1,0]
	v_pk_mul_f32 v[104:105], v[104:105], v[168:169] op_sel_hi:[1,0]
	v_pk_mul_f32 v[106:107], v[106:107], v[168:169] op_sel_hi:[1,0]
	v_pk_mul_f32 v[100:101], v[100:101], v[168:169] op_sel_hi:[1,0]
	v_pk_mul_f32 v[102:103], v[102:103], v[168:169] op_sel_hi:[1,0]
	v_pk_mul_f32 v[96:97], v[96:97], v[168:169] op_sel_hi:[1,0]
	v_pk_mul_f32 v[98:99], v[98:99], v[168:169] op_sel_hi:[1,0]
	v_max_f32_e32 v108, 0, v108
	v_max_f32_e32 v109, 0, v109
	v_max_f32_e32 v110, 0, v110
	v_max_f32_e32 v111, 0, v111
	v_max_f32_e32 v104, 0, v104
	v_max_f32_e32 v105, 0, v105
	v_max_f32_e32 v106, 0, v106
	v_max_f32_e32 v107, 0, v107
	v_max_f32_e32 v100, 0, v100
	v_max_f32_e32 v101, 0, v101
	v_max_f32_e32 v102, 0, v102
	v_max_f32_e32 v103, 0, v103
	v_max_f32_e32 v96, 0, v96
	v_max_f32_e32 v97, 0, v97
	v_max_f32_e32 v98, 0, v98
	v_max_f32_e32 v99, 0, v99
	v_pk_mul_f32 v[108:109], v[108:109], v[108:109]
	v_pk_mul_f32 v[110:111], v[110:111], v[110:111]
	v_pk_mul_f32 v[104:105], v[104:105], v[104:105]
	v_pk_mul_f32 v[106:107], v[106:107], v[106:107]
	v_pk_mul_f32 v[100:101], v[100:101], v[100:101]
	v_pk_mul_f32 v[102:103], v[102:103], v[102:103]
	v_pk_mul_f32 v[96:97], v[96:97], v[96:97]
	v_pk_mul_f32 v[98:99], v[98:99], v[98:99]
	v_cvt_pk_bf16_f32 v108, v108, v109
	v_cvt_pk_bf16_f32 v109, v110, v111
	v_cvt_pk_bf16_f32 v110, v104, v105
	v_cvt_pk_bf16_f32 v111, v106, v107
	v_cvt_pk_bf16_f32 v100, v100, v101
	v_cvt_pk_bf16_f32 v101, v102, v103
	v_cvt_pk_bf16_f32 v102, v96, v97
	v_cvt_pk_bf16_f32 v103, v98, v99
	v_add_u32_e32 v225, 0x20000, v224
	global_store_dwordx4 v225, v[108:111], s[48:49]
	global_store_dwordx4 v225, v[100:103], s[48:49] offset:256
	s_waitcnt vmcnt(9)
	v_fmamk_f32 v170, v170, 0x3a800000, v148
	v_rsq_f32_e32 v170, v170
	s_nop 0
	v_pk_mul_f32 v[92:93], v[92:93], v[170:171] op_sel_hi:[1,0]
	v_pk_mul_f32 v[94:95], v[94:95], v[170:171] op_sel_hi:[1,0]
	v_pk_mul_f32 v[88:89], v[88:89], v[170:171] op_sel_hi:[1,0]
	v_pk_mul_f32 v[90:91], v[90:91], v[170:171] op_sel_hi:[1,0]
	v_pk_mul_f32 v[84:85], v[84:85], v[170:171] op_sel_hi:[1,0]
	v_pk_mul_f32 v[86:87], v[86:87], v[170:171] op_sel_hi:[1,0]
	v_pk_mul_f32 v[80:81], v[80:81], v[170:171] op_sel_hi:[1,0]
	v_pk_mul_f32 v[82:83], v[82:83], v[170:171] op_sel_hi:[1,0]
	v_max_f32_e32 v92, 0, v92
	v_max_f32_e32 v93, 0, v93
	v_max_f32_e32 v94, 0, v94
	v_max_f32_e32 v95, 0, v95
	v_max_f32_e32 v88, 0, v88
	v_max_f32_e32 v89, 0, v89
	v_max_f32_e32 v90, 0, v90
	v_max_f32_e32 v91, 0, v91
	v_max_f32_e32 v84, 0, v84
	v_max_f32_e32 v85, 0, v85
	v_max_f32_e32 v86, 0, v86
	v_max_f32_e32 v87, 0, v87
	v_max_f32_e32 v80, 0, v80
	v_max_f32_e32 v81, 0, v81
	v_max_f32_e32 v82, 0, v82
	v_max_f32_e32 v83, 0, v83
	v_pk_mul_f32 v[92:93], v[92:93], v[92:93]
	v_pk_mul_f32 v[94:95], v[94:95], v[94:95]
	v_pk_mul_f32 v[88:89], v[88:89], v[88:89]
	v_pk_mul_f32 v[90:91], v[90:91], v[90:91]
	v_pk_mul_f32 v[84:85], v[84:85], v[84:85]
	v_pk_mul_f32 v[86:87], v[86:87], v[86:87]
	v_pk_mul_f32 v[80:81], v[80:81], v[80:81]
	v_pk_mul_f32 v[82:83], v[82:83], v[82:83]
	v_cvt_pk_bf16_f32 v92, v92, v93
	v_cvt_pk_bf16_f32 v93, v94, v95
	v_cvt_pk_bf16_f32 v94, v88, v89
	v_cvt_pk_bf16_f32 v95, v90, v91
	v_cvt_pk_bf16_f32 v84, v84, v85
	v_cvt_pk_bf16_f32 v85, v86, v87
	v_cvt_pk_bf16_f32 v86, v80, v81
	v_cvt_pk_bf16_f32 v87, v82, v83
	v_add_u32_e32 v225, 0x40000, v224
	global_store_dwordx4 v225, v[92:95], s[48:49]
	global_store_dwordx4 v225, v[84:87], s[48:49] offset:256
	s_waitcnt vmcnt(10)
	v_fmamk_f32 v172, v172, 0x3a800000, v148
	v_rsq_f32_e32 v172, v172
	s_nop 0
	v_pk_mul_f32 v[76:77], v[76:77], v[172:173] op_sel_hi:[1,0]
	v_pk_mul_f32 v[78:79], v[78:79], v[172:173] op_sel_hi:[1,0]
	v_pk_mul_f32 v[72:73], v[72:73], v[172:173] op_sel_hi:[1,0]
	v_pk_mul_f32 v[74:75], v[74:75], v[172:173] op_sel_hi:[1,0]
	v_pk_mul_f32 v[68:69], v[68:69], v[172:173] op_sel_hi:[1,0]
	v_pk_mul_f32 v[70:71], v[70:71], v[172:173] op_sel_hi:[1,0]
	v_pk_mul_f32 v[64:65], v[64:65], v[172:173] op_sel_hi:[1,0]
	v_pk_mul_f32 v[66:67], v[66:67], v[172:173] op_sel_hi:[1,0]
	v_max_f32_e32 v76, 0, v76
	v_max_f32_e32 v77, 0, v77
	v_max_f32_e32 v78, 0, v78
	v_max_f32_e32 v79, 0, v79
	v_max_f32_e32 v72, 0, v72
	v_max_f32_e32 v73, 0, v73
	v_max_f32_e32 v74, 0, v74
	v_max_f32_e32 v75, 0, v75
	v_max_f32_e32 v68, 0, v68
	v_max_f32_e32 v69, 0, v69
	v_max_f32_e32 v70, 0, v70
	v_max_f32_e32 v71, 0, v71
	v_max_f32_e32 v64, 0, v64
	v_max_f32_e32 v65, 0, v65
	v_max_f32_e32 v66, 0, v66
	v_max_f32_e32 v67, 0, v67
	v_pk_mul_f32 v[76:77], v[76:77], v[76:77]
	v_pk_mul_f32 v[78:79], v[78:79], v[78:79]
	v_pk_mul_f32 v[72:73], v[72:73], v[72:73]
	v_pk_mul_f32 v[74:75], v[74:75], v[74:75]
	v_pk_mul_f32 v[68:69], v[68:69], v[68:69]
	v_pk_mul_f32 v[70:71], v[70:71], v[70:71]
	v_pk_mul_f32 v[64:65], v[64:65], v[64:65]
	v_pk_mul_f32 v[66:67], v[66:67], v[66:67]
	v_cvt_pk_bf16_f32 v76, v76, v77
	v_cvt_pk_bf16_f32 v77, v78, v79
	v_cvt_pk_bf16_f32 v78, v72, v73
	v_cvt_pk_bf16_f32 v79, v74, v75
	v_cvt_pk_bf16_f32 v68, v68, v69
	v_cvt_pk_bf16_f32 v69, v70, v71
	v_cvt_pk_bf16_f32 v70, v64, v65
	v_cvt_pk_bf16_f32 v71, v66, v67
	v_add_u32_e32 v225, 0x60000, v224
	global_store_dwordx4 v225, v[76:79], s[48:49]
	global_store_dwordx4 v225, v[68:71], s[48:49] offset:256
	s_waitcnt vmcnt(11)
	v_fmamk_f32 v174, v174, 0x3a800000, v148
	v_rsq_f32_e32 v174, v174
	s_nop 0
	v_pk_mul_f32 v[60:61], v[60:61], v[174:175] op_sel_hi:[1,0]
	v_pk_mul_f32 v[62:63], v[62:63], v[174:175] op_sel_hi:[1,0]
	v_pk_mul_f32 v[56:57], v[56:57], v[174:175] op_sel_hi:[1,0]
	v_pk_mul_f32 v[58:59], v[58:59], v[174:175] op_sel_hi:[1,0]
	v_pk_mul_f32 v[52:53], v[52:53], v[174:175] op_sel_hi:[1,0]
	v_pk_mul_f32 v[54:55], v[54:55], v[174:175] op_sel_hi:[1,0]
	v_pk_mul_f32 v[48:49], v[48:49], v[174:175] op_sel_hi:[1,0]
	v_pk_mul_f32 v[50:51], v[50:51], v[174:175] op_sel_hi:[1,0]
	v_max_f32_e32 v60, 0, v60
	v_max_f32_e32 v61, 0, v61
	v_max_f32_e32 v62, 0, v62
	v_max_f32_e32 v63, 0, v63
	v_max_f32_e32 v56, 0, v56
	v_max_f32_e32 v57, 0, v57
	v_max_f32_e32 v58, 0, v58
	v_max_f32_e32 v59, 0, v59
	v_max_f32_e32 v52, 0, v52
	v_max_f32_e32 v53, 0, v53
	v_max_f32_e32 v54, 0, v54
	v_max_f32_e32 v55, 0, v55
	v_max_f32_e32 v48, 0, v48
	v_max_f32_e32 v49, 0, v49
	v_max_f32_e32 v50, 0, v50
	v_max_f32_e32 v51, 0, v51
	v_pk_mul_f32 v[60:61], v[60:61], v[60:61]
	v_pk_mul_f32 v[62:63], v[62:63], v[62:63]
	v_pk_mul_f32 v[56:57], v[56:57], v[56:57]
	v_pk_mul_f32 v[58:59], v[58:59], v[58:59]
	v_pk_mul_f32 v[52:53], v[52:53], v[52:53]
	v_pk_mul_f32 v[54:55], v[54:55], v[54:55]
	v_pk_mul_f32 v[48:49], v[48:49], v[48:49]
	v_pk_mul_f32 v[50:51], v[50:51], v[50:51]
	v_cvt_pk_bf16_f32 v60, v60, v61
	v_cvt_pk_bf16_f32 v61, v62, v63
	v_cvt_pk_bf16_f32 v62, v56, v57
	v_cvt_pk_bf16_f32 v63, v58, v59
	v_cvt_pk_bf16_f32 v52, v52, v53
	v_cvt_pk_bf16_f32 v53, v54, v55
	v_cvt_pk_bf16_f32 v54, v48, v49
	v_cvt_pk_bf16_f32 v55, v50, v51
	v_add_u32_e32 v225, 0x100000, v224
	global_store_dwordx4 v225, v[60:63], s[48:49]
	global_store_dwordx4 v225, v[52:55], s[48:49] offset:256
	s_waitcnt vmcnt(12)
	v_fmamk_f32 v176, v176, 0x3a800000, v148
	v_rsq_f32_e32 v176, v176
	s_nop 0
	v_pk_mul_f32 v[44:45], v[44:45], v[176:177] op_sel_hi:[1,0]
	v_pk_mul_f32 v[46:47], v[46:47], v[176:177] op_sel_hi:[1,0]
	v_pk_mul_f32 v[40:41], v[40:41], v[176:177] op_sel_hi:[1,0]
	v_pk_mul_f32 v[42:43], v[42:43], v[176:177] op_sel_hi:[1,0]
	v_pk_mul_f32 v[36:37], v[36:37], v[176:177] op_sel_hi:[1,0]
	v_pk_mul_f32 v[38:39], v[38:39], v[176:177] op_sel_hi:[1,0]
	v_pk_mul_f32 v[32:33], v[32:33], v[176:177] op_sel_hi:[1,0]
	v_pk_mul_f32 v[34:35], v[34:35], v[176:177] op_sel_hi:[1,0]
	v_max_f32_e32 v44, 0, v44
	v_max_f32_e32 v45, 0, v45
	v_max_f32_e32 v46, 0, v46
	v_max_f32_e32 v47, 0, v47
	v_max_f32_e32 v40, 0, v40
	v_max_f32_e32 v41, 0, v41
	v_max_f32_e32 v42, 0, v42
	v_max_f32_e32 v43, 0, v43
	v_max_f32_e32 v36, 0, v36
	v_max_f32_e32 v37, 0, v37
	v_max_f32_e32 v38, 0, v38
	v_max_f32_e32 v39, 0, v39
	v_max_f32_e32 v32, 0, v32
	v_max_f32_e32 v33, 0, v33
	v_max_f32_e32 v34, 0, v34
	v_max_f32_e32 v35, 0, v35
	v_pk_mul_f32 v[44:45], v[44:45], v[44:45]
	v_pk_mul_f32 v[46:47], v[46:47], v[46:47]
	v_pk_mul_f32 v[40:41], v[40:41], v[40:41]
	v_pk_mul_f32 v[42:43], v[42:43], v[42:43]
	v_pk_mul_f32 v[36:37], v[36:37], v[36:37]
	v_pk_mul_f32 v[38:39], v[38:39], v[38:39]
	v_pk_mul_f32 v[32:33], v[32:33], v[32:33]
	v_pk_mul_f32 v[34:35], v[34:35], v[34:35]
	v_cvt_pk_bf16_f32 v44, v44, v45
	v_cvt_pk_bf16_f32 v45, v46, v47
	v_cvt_pk_bf16_f32 v46, v40, v41
	v_cvt_pk_bf16_f32 v47, v42, v43
	v_cvt_pk_bf16_f32 v36, v36, v37
	v_cvt_pk_bf16_f32 v37, v38, v39
	v_cvt_pk_bf16_f32 v38, v32, v33
	v_cvt_pk_bf16_f32 v39, v34, v35
	v_add_u32_e32 v225, 0x120000, v224
	global_store_dwordx4 v225, v[44:47], s[48:49]
	global_store_dwordx4 v225, v[36:39], s[48:49] offset:256
	s_waitcnt vmcnt(13)
	v_fmamk_f32 v178, v178, 0x3a800000, v148
	v_rsq_f32_e32 v178, v178
	s_nop 0
	v_pk_mul_f32 v[28:29], v[28:29], v[178:179] op_sel_hi:[1,0]
	v_pk_mul_f32 v[30:31], v[30:31], v[178:179] op_sel_hi:[1,0]
	v_pk_mul_f32 v[24:25], v[24:25], v[178:179] op_sel_hi:[1,0]
	v_pk_mul_f32 v[26:27], v[26:27], v[178:179] op_sel_hi:[1,0]
	v_pk_mul_f32 v[20:21], v[20:21], v[178:179] op_sel_hi:[1,0]
	v_pk_mul_f32 v[22:23], v[22:23], v[178:179] op_sel_hi:[1,0]
	v_pk_mul_f32 v[16:17], v[16:17], v[178:179] op_sel_hi:[1,0]
	v_pk_mul_f32 v[18:19], v[18:19], v[178:179] op_sel_hi:[1,0]
	v_max_f32_e32 v28, 0, v28
	v_max_f32_e32 v29, 0, v29
	v_max_f32_e32 v30, 0, v30
	v_max_f32_e32 v31, 0, v31
	v_max_f32_e32 v24, 0, v24
	v_max_f32_e32 v25, 0, v25
	v_max_f32_e32 v26, 0, v26
	v_max_f32_e32 v27, 0, v27
	v_max_f32_e32 v20, 0, v20
	v_max_f32_e32 v21, 0, v21
	v_max_f32_e32 v22, 0, v22
	v_max_f32_e32 v23, 0, v23
	v_max_f32_e32 v16, 0, v16
	v_max_f32_e32 v17, 0, v17
	v_max_f32_e32 v18, 0, v18
	v_max_f32_e32 v19, 0, v19
	v_pk_mul_f32 v[28:29], v[28:29], v[28:29]
	v_pk_mul_f32 v[30:31], v[30:31], v[30:31]
	v_pk_mul_f32 v[24:25], v[24:25], v[24:25]
	v_pk_mul_f32 v[26:27], v[26:27], v[26:27]
	v_pk_mul_f32 v[20:21], v[20:21], v[20:21]
	v_pk_mul_f32 v[22:23], v[22:23], v[22:23]
	v_pk_mul_f32 v[16:17], v[16:17], v[16:17]
	v_pk_mul_f32 v[18:19], v[18:19], v[18:19]
	v_cvt_pk_bf16_f32 v28, v28, v29
	v_cvt_pk_bf16_f32 v29, v30, v31
	v_cvt_pk_bf16_f32 v30, v24, v25
	v_cvt_pk_bf16_f32 v31, v26, v27
	v_cvt_pk_bf16_f32 v20, v20, v21
	v_cvt_pk_bf16_f32 v21, v22, v23
	v_cvt_pk_bf16_f32 v22, v16, v17
	v_cvt_pk_bf16_f32 v23, v18, v19
	v_add_u32_e32 v225, 0x140000, v224
	global_store_dwordx4 v225, v[28:31], s[48:49]
	global_store_dwordx4 v225, v[20:23], s[48:49] offset:256
	s_waitcnt vmcnt(14)
	v_fmamk_f32 v180, v180, 0x3a800000, v148
	v_rsq_f32_e32 v180, v180
	s_nop 0
	v_pk_mul_f32 v[12:13], v[12:13], v[180:181] op_sel_hi:[1,0]
	v_pk_mul_f32 v[14:15], v[14:15], v[180:181] op_sel_hi:[1,0]
	v_pk_mul_f32 v[8:9], v[8:9], v[180:181] op_sel_hi:[1,0]
	v_pk_mul_f32 v[10:11], v[10:11], v[180:181] op_sel_hi:[1,0]
	v_pk_mul_f32 v[4:5], v[4:5], v[180:181] op_sel_hi:[1,0]
	v_pk_mul_f32 v[6:7], v[6:7], v[180:181] op_sel_hi:[1,0]
	v_pk_mul_f32 v[0:1], v[0:1], v[180:181] op_sel_hi:[1,0]
	v_pk_mul_f32 v[2:3], v[2:3], v[180:181] op_sel_hi:[1,0]
	v_max_f32_e32 v12, 0, v12
	v_max_f32_e32 v13, 0, v13
	v_max_f32_e32 v14, 0, v14
	v_max_f32_e32 v15, 0, v15
	v_max_f32_e32 v8, 0, v8
	v_max_f32_e32 v9, 0, v9
	v_max_f32_e32 v10, 0, v10
	v_max_f32_e32 v11, 0, v11
	v_max_f32_e32 v4, 0, v4
	v_max_f32_e32 v5, 0, v5
	v_max_f32_e32 v6, 0, v6
	v_max_f32_e32 v7, 0, v7
	v_max_f32_e32 v0, 0, v0
	v_max_f32_e32 v1, 0, v1
	v_max_f32_e32 v2, 0, v2
	v_max_f32_e32 v3, 0, v3
	v_pk_mul_f32 v[12:13], v[12:13], v[12:13]
	v_pk_mul_f32 v[14:15], v[14:15], v[14:15]
	v_pk_mul_f32 v[8:9], v[8:9], v[8:9]
	v_pk_mul_f32 v[10:11], v[10:11], v[10:11]
	v_pk_mul_f32 v[4:5], v[4:5], v[4:5]
	v_pk_mul_f32 v[6:7], v[6:7], v[6:7]
	v_pk_mul_f32 v[0:1], v[0:1], v[0:1]
	v_pk_mul_f32 v[2:3], v[2:3], v[2:3]
	v_cvt_pk_bf16_f32 v12, v12, v13
	v_cvt_pk_bf16_f32 v13, v14, v15
	v_cvt_pk_bf16_f32 v14, v8, v9
	v_cvt_pk_bf16_f32 v15, v10, v11
	v_cvt_pk_bf16_f32 v4, v4, v5
	v_cvt_pk_bf16_f32 v5, v6, v7
	v_cvt_pk_bf16_f32 v6, v0, v1
	v_cvt_pk_bf16_f32 v7, v2, v3
	v_add_u32_e32 v225, 0x160000, v224
	global_store_dwordx4 v225, v[12:15], s[48:49]
	global_store_dwordx4 v225, v[4:7], s[48:49] offset:256
	s_mov_b32 s11, 0x160000
	s_andn2_b64 vcc, exec, s[36:37]
	s_mov_b64 s[14:15], -1
	s_cbranch_vccnz .LBB0_656
	s_andn2_b64 vcc, exec, s[4:5]
	s_cbranch_vccnz .LBB0_655
	s_barrier
	s_branch .LBB0_655
